# grid barrier after phases 2..17: every workgroup polls the cross-XCD arrival counter directly (no release-generation hops)
# speedup vs baseline: 1.0117x; 1.0117x over previous
.LBB0_331:
	s_waitcnt vmcnt(0)
	s_waitcnt lgkmcnt(0)
	s_barrier
	s_mov_b64 s[4:5], exec
	v_readlane_b32 s0, v126, 10
	v_readlane_b32 s1, v126, 11
	s_and_b64 s[0:1], s[4:5], s[0:1]
	s_mov_b64 exec, s[0:1]
	s_cbranch_execz .LBB0_383
	v_readlane_b32 s8, v126, 12
	v_readlane_b32 s9, v126, 13
	v_readlane_b32 s3, v126, 14
	v_mov_b32_e32 v0, 0
	v_mov_b32_e32 v1, 1
	s_lshl_b32 s3, s3, 8
	s_add_u32 s0, s8, s3
	s_addc_u32 s1, s9, 0
	s_add_u32 s0, s0, 0x1400
	s_addc_u32 s1, s1, 0
	global_atomic_add v4, v0, v1, s[0:1] sc0
	v_mov_b32_e32 v5, 0x23ff0
	ds_read2_b32 v[2:3], v5 offset1:1
	s_add_u32 s8, s8, 0x3400
	s_addc_u32 s9, s9, 0
	s_sub_i32 s3, 3, s90
	s_mov_b32 s7, 0
	s_waitcnt lgkmcnt(0)
	v_readfirstlane_b32 s1, v2
	v_readfirstlane_b32 s6, v3
	s_mul_i32 s1, s1, s3
	s_mul_i32 s6, s6, s3
	s_waitcnt vmcnt(0)
	v_readfirstlane_b32 s0, v4
	s_add_i32 s0, s0, 1
	s_cmp_lg_u32 s0, s1
	s_cbranch_scc1 .Lgb2_poll
	buffer_wbl2 sc1
	s_waitcnt vmcnt(0)
	global_atomic_add v0, v1, s[8:9]
.Lgb2_poll:
	global_load_dword v4, v0, s[8:9] sc1
	s_waitcnt vmcnt(0)
	v_readfirstlane_b32 s0, v4
	s_sub_i32 s0, s0, s6
	s_cmp_ge_i32 s0, 0
	s_cbranch_scc1 .Lgb2_rel
	s_add_i32 s7, s7, 1
	s_sleep 1
	s_cmp_lt_u32 s7, 0x2000
	s_cbranch_scc1 .Lgb2_poll
.Lgb2_rel:
	buffer_inv sc1
	s_waitcnt vmcnt(0)

.LBB0_535:
	s_cmp_lt_i32 s91, 5
	s_cbranch_scc1 .LBB0_589
	s_waitcnt vmcnt(0)
	s_waitcnt lgkmcnt(0)
	s_barrier
	s_mov_b64 s[4:5], exec
	v_readlane_b32 s0, v126, 10
	v_readlane_b32 s1, v126, 11
	s_and_b64 s[0:1], s[4:5], s[0:1]
	s_mov_b64 exec, s[0:1]
	s_cbranch_execz .LBB0_588
	v_readlane_b32 s8, v126, 12
	v_readlane_b32 s9, v126, 13
	v_readlane_b32 s3, v126, 14
	v_mov_b32_e32 v0, 0
	v_mov_b32_e32 v1, 1
	s_lshl_b32 s3, s3, 8
	s_add_u32 s0, s8, s3
	s_addc_u32 s1, s9, 0
	s_add_u32 s0, s0, 0x1400
	s_addc_u32 s1, s1, 0
	global_atomic_add v4, v0, v1, s[0:1] sc0
	v_mov_b32_e32 v5, 0x23ff0
	ds_read2_b32 v[2:3], v5 offset1:1
	s_add_u32 s8, s8, 0x3400
	s_addc_u32 s9, s9, 0
	s_sub_i32 s3, 4, s90
	s_mov_b32 s7, 0
	s_waitcnt lgkmcnt(0)
	v_readfirstlane_b32 s1, v2
	v_readfirstlane_b32 s6, v3
	s_mul_i32 s1, s1, s3
	s_mul_i32 s6, s6, s3
	s_waitcnt vmcnt(0)
	v_readfirstlane_b32 s0, v4
	s_add_i32 s0, s0, 1
	s_cmp_lg_u32 s0, s1
	s_cbranch_scc1 .Lgb3_poll
	buffer_wbl2 sc1
	s_waitcnt vmcnt(0)
	global_atomic_add v0, v1, s[8:9]

.LBB0_611:
	s_cmp_lt_i32 s91, 6
	s_cbranch_scc1 .LBB0_665
	s_waitcnt vmcnt(0)
	s_waitcnt lgkmcnt(0)
	s_barrier
	s_mov_b64 s[6:7], exec
	v_readlane_b32 s0, v126, 10
	v_readlane_b32 s1, v126, 11
	s_and_b64 s[0:1], s[6:7], s[0:1]
	s_mov_b64 exec, s[0:1]
	s_cbranch_execz .LBB0_664
	v_readlane_b32 s8, v126, 12
	v_readlane_b32 s9, v126, 13
	v_readlane_b32 s3, v126, 14
	v_mov_b32_e32 v0, 0
	v_mov_b32_e32 v1, 1
	s_lshl_b32 s3, s3, 8
	s_add_u32 s0, s8, s3
	s_addc_u32 s1, s9, 0
	s_add_u32 s0, s0, 0x1400
	s_addc_u32 s1, s1, 0
	global_atomic_add v4, v0, v1, s[0:1] sc0
	v_mov_b32_e32 v5, 0x23ff0
	ds_read2_b32 v[2:3], v5 offset1:1
	s_add_u32 s8, s8, 0x3400
	s_addc_u32 s9, s9, 0
	s_sub_i32 s3, 5, s90
	s_mov_b32 s5, 0
	s_waitcnt lgkmcnt(0)
	v_readfirstlane_b32 s1, v2
	v_readfirstlane_b32 s4, v3
	s_mul_i32 s1, s1, s3
	s_mul_i32 s4, s4, s3
	s_waitcnt vmcnt(0)
	v_readfirstlane_b32 s0, v4
	s_add_i32 s0, s0, 1
	s_cmp_lg_u32 s0, s1
	s_cbranch_scc1 .Lgb4_poll
	buffer_wbl2 sc1
	s_waitcnt vmcnt(0)
	global_atomic_add v0, v1, s[8:9]
.Lgb4_poll:
	global_load_dword v4, v0, s[8:9] sc1
	s_waitcnt vmcnt(0)
	v_readfirstlane_b32 s0, v4
	s_sub_i32 s0, s0, s4
	s_cmp_ge_i32 s0, 0
	s_cbranch_scc1 .Lgb4_rel
	s_add_i32 s5, s5, 1
	s_sleep 1
	s_cmp_lt_u32 s5, 0x2000
	s_cbranch_scc1 .Lgb4_poll

.LBB0_690:
	s_cmp_lt_i32 s91, 7
	s_cbranch_scc1 .LBB0_744
	s_waitcnt vmcnt(0)
	s_waitcnt lgkmcnt(0)
	s_barrier
	s_mov_b64 s[4:5], exec
	v_readlane_b32 s0, v126, 10
	v_readlane_b32 s1, v126, 11
	s_and_b64 s[0:1], s[4:5], s[0:1]
	s_mov_b64 exec, s[0:1]
	s_cbranch_execz .LBB0_743
	v_readlane_b32 s8, v126, 12
	v_readlane_b32 s9, v126, 13
	v_readlane_b32 s3, v126, 14
	v_mov_b32_e32 v0, 0
	v_mov_b32_e32 v1, 1
	s_lshl_b32 s3, s3, 8
	s_add_u32 s0, s8, s3
	s_addc_u32 s1, s9, 0
	s_add_u32 s0, s0, 0x1400
	s_addc_u32 s1, s1, 0
	global_atomic_add v4, v0, v1, s[0:1] sc0
	v_mov_b32_e32 v5, 0x23ff0
	ds_read2_b32 v[2:3], v5 offset1:1
	s_add_u32 s8, s8, 0x3400
	s_addc_u32 s9, s9, 0
	s_sub_i32 s3, 6, s90
	s_mov_b32 s7, 0
	s_waitcnt lgkmcnt(0)
	v_readfirstlane_b32 s1, v2
	v_readfirstlane_b32 s6, v3
	s_mul_i32 s1, s1, s3
	s_mul_i32 s6, s6, s3
	s_waitcnt vmcnt(0)
	v_readfirstlane_b32 s0, v4
	s_add_i32 s0, s0, 1
	s_cmp_lg_u32 s0, s1
	s_cbranch_scc1 .Lgb5_poll
	buffer_wbl2 sc1
	s_waitcnt vmcnt(0)
	global_atomic_add v0, v1, s[8:9]

.LBB0_755:
	s_cmp_lt_i32 s91, 8
	s_cbranch_scc1 .LBB0_809
	s_waitcnt vmcnt(0)
	s_waitcnt lgkmcnt(0)
	s_barrier
	s_mov_b64 s[4:5], exec
	v_readlane_b32 s0, v126, 10
	v_readlane_b32 s1, v126, 11
	s_and_b64 s[0:1], s[4:5], s[0:1]
	s_mov_b64 exec, s[0:1]
	s_cbranch_execz .LBB0_808
	v_readlane_b32 s8, v126, 12
	v_readlane_b32 s9, v126, 13
	v_readlane_b32 s3, v126, 14
	v_mov_b32_e32 v0, 0
	v_mov_b32_e32 v1, 1
	s_lshl_b32 s3, s3, 8
	s_add_u32 s0, s8, s3
	s_addc_u32 s1, s9, 0
	s_add_u32 s0, s0, 0x1400
	s_addc_u32 s1, s1, 0
	global_atomic_add v4, v0, v1, s[0:1] sc0
	v_mov_b32_e32 v5, 0x23ff0
	ds_read2_b32 v[2:3], v5 offset1:1
	s_add_u32 s8, s8, 0x3400
	s_addc_u32 s9, s9, 0
	s_sub_i32 s3, 7, s90
	s_mov_b32 s7, 0
	s_waitcnt lgkmcnt(0)
	v_readfirstlane_b32 s1, v2
	v_readfirstlane_b32 s6, v3
	s_mul_i32 s1, s1, s3
	s_mul_i32 s6, s6, s3
	s_waitcnt vmcnt(0)
	v_readfirstlane_b32 s0, v4
	s_add_i32 s0, s0, 1
	s_cmp_lg_u32 s0, s1
	s_cbranch_scc1 .Lgb6_poll
	buffer_wbl2 sc1
	s_waitcnt vmcnt(0)
	global_atomic_add v0, v1, s[8:9]

.LBB0_849:
	s_cmp_lt_i32 s91, 9
	s_cbranch_scc1 .LBB0_903
	s_waitcnt vmcnt(0)
	s_waitcnt lgkmcnt(0)
	s_barrier
	s_mov_b64 s[4:5], exec
	v_readlane_b32 s0, v126, 10
	v_readlane_b32 s1, v126, 11
	s_and_b64 s[0:1], s[4:5], s[0:1]
	s_mov_b64 exec, s[0:1]
	s_cbranch_execz .LBB0_902
	v_readlane_b32 s8, v126, 12
	v_readlane_b32 s9, v126, 13
	v_readlane_b32 s3, v126, 14
	v_mov_b32_e32 v0, 0
	v_mov_b32_e32 v1, 1
	s_lshl_b32 s3, s3, 8
	s_add_u32 s0, s8, s3
	s_addc_u32 s1, s9, 0
	s_add_u32 s0, s0, 0x1400
	s_addc_u32 s1, s1, 0
	global_atomic_add v4, v0, v1, s[0:1] sc0
	v_mov_b32_e32 v5, 0x23ff0
	ds_read2_b32 v[2:3], v5 offset1:1
	s_add_u32 s8, s8, 0x3400
	s_addc_u32 s9, s9, 0
	s_sub_i32 s3, 8, s90
	s_mov_b32 s7, 0
	s_waitcnt lgkmcnt(0)
	v_readfirstlane_b32 s1, v2
	v_readfirstlane_b32 s6, v3
	s_mul_i32 s1, s1, s3
	s_mul_i32 s6, s6, s3
	s_waitcnt vmcnt(0)
	v_readfirstlane_b32 s0, v4
	s_add_i32 s0, s0, 1
	s_cmp_lg_u32 s0, s1
	s_cbranch_scc1 .Lgb7_poll
	buffer_wbl2 sc1
	s_waitcnt vmcnt(0)
	global_atomic_add v0, v1, s[8:9]

.LBB0_920:
	s_cmp_lt_i32 s91, 10
	s_cbranch_scc1 .LBB0_974
	s_waitcnt vmcnt(0)
	s_waitcnt vmcnt(0) lgkmcnt(0)
	s_barrier
	s_mov_b64 s[4:5], exec
	v_readlane_b32 s0, v126, 10
	v_readlane_b32 s1, v126, 11
	s_and_b64 s[0:1], s[4:5], s[0:1]
	s_mov_b64 exec, s[0:1]
	s_cbranch_execz .LBB0_973
	v_readlane_b32 s8, v126, 12
	v_readlane_b32 s9, v126, 13
	v_readlane_b32 s3, v126, 14
	v_mov_b32_e32 v0, 0
	v_mov_b32_e32 v1, 1
	s_lshl_b32 s3, s3, 8
	s_add_u32 s0, s8, s3
	s_addc_u32 s1, s9, 0
	s_add_u32 s0, s0, 0x1400
	s_addc_u32 s1, s1, 0
	global_atomic_add v4, v0, v1, s[0:1] sc0
	v_mov_b32_e32 v5, 0x23ff0
	ds_read2_b32 v[2:3], v5 offset1:1
	s_add_u32 s8, s8, 0x3400
	s_addc_u32 s9, s9, 0
	s_sub_i32 s3, 9, s90
	s_mov_b32 s7, 0
	s_waitcnt lgkmcnt(0)
	v_readfirstlane_b32 s1, v2
	v_readfirstlane_b32 s6, v3
	s_mul_i32 s1, s1, s3
	s_mul_i32 s6, s6, s3
	s_waitcnt vmcnt(0)
	v_readfirstlane_b32 s0, v4
	s_add_i32 s0, s0, 1
	s_cmp_lg_u32 s0, s1
	s_cbranch_scc1 .Lgb8_poll
	buffer_wbl2 sc1
	s_waitcnt vmcnt(0)
	global_atomic_add v0, v1, s[8:9]

.LBB0_991:
	s_cmp_lt_i32 s91, 11
	s_cbranch_scc1 .LBB0_1045
	s_waitcnt vmcnt(0)
	s_waitcnt vmcnt(0) lgkmcnt(0)
	s_barrier
	s_mov_b64 s[4:5], exec
	v_readlane_b32 s0, v126, 10
	v_readlane_b32 s1, v126, 11
	s_and_b64 s[0:1], s[4:5], s[0:1]
	s_mov_b64 exec, s[0:1]
	s_cbranch_execz .LBB0_1044
	v_readlane_b32 s8, v126, 12
	v_readlane_b32 s9, v126, 13
	v_readlane_b32 s3, v126, 14
	v_mov_b32_e32 v0, 0
	v_mov_b32_e32 v1, 1
	s_lshl_b32 s3, s3, 8
	s_add_u32 s0, s8, s3
	s_addc_u32 s1, s9, 0
	s_add_u32 s0, s0, 0x1400
	s_addc_u32 s1, s1, 0
	global_atomic_add v4, v0, v1, s[0:1] sc0
	v_mov_b32_e32 v5, 0x23ff0
	ds_read2_b32 v[2:3], v5 offset1:1
	s_add_u32 s8, s8, 0x3400
	s_addc_u32 s9, s9, 0
	s_sub_i32 s3, 10, s90
	s_mov_b32 s7, 0
	s_waitcnt lgkmcnt(0)
	v_readfirstlane_b32 s1, v2
	v_readfirstlane_b32 s6, v3
	s_mul_i32 s1, s1, s3
	s_mul_i32 s6, s6, s3
	s_waitcnt vmcnt(0)
	v_readfirstlane_b32 s0, v4
	s_add_i32 s0, s0, 1
	s_cmp_lg_u32 s0, s1
	s_cbranch_scc1 .Lgb9_poll
	buffer_wbl2 sc1
	s_waitcnt vmcnt(0)
	global_atomic_add v0, v1, s[8:9]

.LBB0_1055:
	s_or_b64 exec, exec, s[8:9]
	s_cmp_lt_i32 s91, 12
	s_cbranch_scc1 .LBB0_1109
	s_waitcnt vmcnt(0)
	s_waitcnt lgkmcnt(0)
	s_barrier
	s_mov_b64 s[4:5], exec
	v_readlane_b32 s0, v126, 10
	v_readlane_b32 s1, v126, 11
	s_and_b64 s[0:1], s[4:5], s[0:1]
	s_mov_b64 exec, s[0:1]
	s_cbranch_execz .LBB0_1108
	v_readlane_b32 s8, v126, 12
	v_readlane_b32 s9, v126, 13
	v_readlane_b32 s3, v126, 14
	v_mov_b32_e32 v0, 0
	v_mov_b32_e32 v1, 1
	s_lshl_b32 s3, s3, 8
	s_add_u32 s0, s8, s3
	s_addc_u32 s1, s9, 0
	s_add_u32 s0, s0, 0x1400
	s_addc_u32 s1, s1, 0
	global_atomic_add v4, v0, v1, s[0:1] sc0
	v_mov_b32_e32 v5, 0x23ff0
	ds_read2_b32 v[2:3], v5 offset1:1
	s_add_u32 s8, s8, 0x3400
	s_addc_u32 s9, s9, 0
	s_sub_i32 s3, 11, s90
	s_mov_b32 s7, 0
	s_waitcnt lgkmcnt(0)
	v_readfirstlane_b32 s1, v2
	v_readfirstlane_b32 s6, v3
	s_mul_i32 s1, s1, s3
	s_mul_i32 s6, s6, s3
	s_waitcnt vmcnt(0)
	v_readfirstlane_b32 s0, v4
	s_add_i32 s0, s0, 1
	s_cmp_lg_u32 s0, s1
	s_cbranch_scc1 .Lgb10_poll
	buffer_wbl2 sc1
	s_waitcnt vmcnt(0)
	global_atomic_add v0, v1, s[8:9]

.LBB0_1153:
	s_waitcnt vmcnt(0)
	s_waitcnt vmcnt(0) lgkmcnt(0)
	s_barrier
	s_mov_b64 s[4:5], exec
	v_readlane_b32 s0, v126, 10
	v_readlane_b32 s1, v126, 11
	s_and_b64 s[0:1], s[4:5], s[0:1]
	s_mov_b64 exec, s[0:1]
	s_cbranch_execz .LBB0_1205
	v_readlane_b32 s8, v126, 12
	v_readlane_b32 s9, v126, 13
	v_readlane_b32 s3, v126, 14
	v_mov_b32_e32 v0, 0
	v_mov_b32_e32 v1, 1
	s_lshl_b32 s3, s3, 8
	s_add_u32 s0, s8, s3
	s_addc_u32 s1, s9, 0
	s_add_u32 s0, s0, 0x1400
	s_addc_u32 s1, s1, 0
	global_atomic_add v4, v0, v1, s[0:1] sc0
	v_mov_b32_e32 v5, 0x23ff0
	ds_read2_b32 v[2:3], v5 offset1:1
	s_add_u32 s8, s8, 0x3400
	s_addc_u32 s9, s9, 0
	s_sub_i32 s3, 12, s90
	s_mov_b32 s7, 0
	s_waitcnt lgkmcnt(0)
	v_readfirstlane_b32 s1, v2
	v_readfirstlane_b32 s6, v3
	s_mul_i32 s1, s1, s3
	s_mul_i32 s6, s6, s3
	s_waitcnt vmcnt(0)
	v_readfirstlane_b32 s0, v4
	s_add_i32 s0, s0, 1
	s_cmp_lg_u32 s0, s1
	s_cbranch_scc1 .Lgb11_poll
	buffer_wbl2 sc1
	s_waitcnt vmcnt(0)
	global_atomic_add v0, v1, s[8:9]

.LBB0_1212:
	s_cmp_lt_i32 s91, 14
	s_cbranch_scc1 .LBB0_1266
	s_waitcnt vmcnt(0)
	s_waitcnt vmcnt(0) lgkmcnt(0)
	s_barrier
	s_mov_b64 s[6:7], exec
	v_readlane_b32 s0, v126, 10
	v_readlane_b32 s1, v126, 11
	s_and_b64 s[0:1], s[6:7], s[0:1]
	s_mov_b64 exec, s[0:1]
	s_cbranch_execz .LBB0_1265
	v_readlane_b32 s8, v126, 12
	v_readlane_b32 s9, v126, 13
	v_readlane_b32 s3, v126, 14
	v_mov_b32_e32 v0, 0
	v_mov_b32_e32 v1, 1
	s_lshl_b32 s3, s3, 8
	s_add_u32 s0, s8, s3
	s_addc_u32 s1, s9, 0
	s_add_u32 s0, s0, 0x1400
	s_addc_u32 s1, s1, 0
	global_atomic_add v4, v0, v1, s[0:1] sc0
	v_mov_b32_e32 v5, 0x23ff0
	ds_read2_b32 v[2:3], v5 offset1:1
	s_add_u32 s8, s8, 0x3400
	s_addc_u32 s9, s9, 0
	s_sub_i32 s3, 13, s90
	s_mov_b32 s5, 0
	s_waitcnt lgkmcnt(0)
	v_readfirstlane_b32 s1, v2
	v_readfirstlane_b32 s4, v3
	s_mul_i32 s1, s1, s3
	s_mul_i32 s4, s4, s3
	s_waitcnt vmcnt(0)
	v_readfirstlane_b32 s0, v4
	s_add_i32 s0, s0, 1
	s_cmp_lg_u32 s0, s1
	s_cbranch_scc1 .Lgb12_poll
	buffer_wbl2 sc1
	s_waitcnt vmcnt(0)
	global_atomic_add v0, v1, s[8:9]

.LBB0_1291:
	s_cmp_lt_i32 s91, 15
	s_cbranch_scc1 .LBB0_1345
	s_waitcnt vmcnt(0)
	s_waitcnt vmcnt(0) lgkmcnt(0)
	s_barrier
	s_mov_b64 s[4:5], exec
	v_readlane_b32 s0, v126, 10
	v_readlane_b32 s1, v126, 11
	s_and_b64 s[0:1], s[4:5], s[0:1]
	s_mov_b64 exec, s[0:1]
	s_cbranch_execz .LBB0_1344
	v_readlane_b32 s8, v126, 12
	v_readlane_b32 s9, v126, 13
	v_readlane_b32 s3, v126, 14
	v_mov_b32_e32 v0, 0
	v_mov_b32_e32 v1, 1
	s_lshl_b32 s3, s3, 8
	s_add_u32 s0, s8, s3
	s_addc_u32 s1, s9, 0
	s_add_u32 s0, s0, 0x1400
	s_addc_u32 s1, s1, 0
	global_atomic_add v4, v0, v1, s[0:1] sc0
	v_mov_b32_e32 v5, 0x23ff0
	ds_read2_b32 v[2:3], v5 offset1:1
	s_add_u32 s8, s8, 0x3400
	s_addc_u32 s9, s9, 0
	s_sub_i32 s3, 14, s90
	s_mov_b32 s7, 0
	s_waitcnt lgkmcnt(0)
	v_readfirstlane_b32 s1, v2
	v_readfirstlane_b32 s6, v3
	s_mul_i32 s1, s1, s3
	s_mul_i32 s6, s6, s3
	s_waitcnt vmcnt(0)
	v_readfirstlane_b32 s0, v4
	s_add_i32 s0, s0, 1
	s_cmp_lg_u32 s0, s1
	s_cbranch_scc1 .Lgb13_poll
	buffer_wbl2 sc1
	s_waitcnt vmcnt(0)
	global_atomic_add v0, v1, s[8:9]

.LBB0_1356:
	s_cmp_lt_i32 s91, 16
	s_cbranch_scc1 .LBB0_1410
	s_waitcnt vmcnt(0)
	s_waitcnt lgkmcnt(0)
	s_barrier
	s_mov_b64 s[4:5], exec
	v_readlane_b32 s0, v126, 10
	v_readlane_b32 s1, v126, 11
	s_and_b64 s[0:1], s[4:5], s[0:1]
	s_mov_b64 exec, s[0:1]
	s_cbranch_execz .LBB0_1409
	v_readlane_b32 s8, v126, 12
	v_readlane_b32 s9, v126, 13
	v_readlane_b32 s3, v126, 14
	v_mov_b32_e32 v0, 0
	v_mov_b32_e32 v1, 1
	s_lshl_b32 s3, s3, 8
	s_add_u32 s0, s8, s3
	s_addc_u32 s1, s9, 0
	s_add_u32 s0, s0, 0x1400
	s_addc_u32 s1, s1, 0
	global_atomic_add v4, v0, v1, s[0:1] sc0
	v_mov_b32_e32 v5, 0x23ff0
	ds_read2_b32 v[2:3], v5 offset1:1
	s_add_u32 s8, s8, 0x3400
	s_addc_u32 s9, s9, 0
	s_sub_i32 s3, 15, s90
	s_mov_b32 s7, 0
	s_waitcnt lgkmcnt(0)
	v_readfirstlane_b32 s1, v2
	v_readfirstlane_b32 s6, v3
	s_mul_i32 s1, s1, s3
	s_mul_i32 s6, s6, s3
	s_waitcnt vmcnt(0)
	v_readfirstlane_b32 s0, v4
	s_add_i32 s0, s0, 1
	s_cmp_lg_u32 s0, s1
	s_cbranch_scc1 .Lgb14_poll
	buffer_wbl2 sc1
	s_waitcnt vmcnt(0)
	global_atomic_add v0, v1, s[8:9]

.LBB0_1450:
	s_cmp_lt_i32 s91, 17
	s_cbranch_scc1 .LBB0_1504
	s_waitcnt vmcnt(0)
	s_waitcnt vmcnt(0) lgkmcnt(0)
	s_barrier
	s_mov_b64 s[4:5], exec
	v_readlane_b32 s0, v126, 10
	v_readlane_b32 s1, v126, 11
	s_and_b64 s[0:1], s[4:5], s[0:1]
	s_mov_b64 exec, s[0:1]
	s_cbranch_execz .LBB0_1503
	v_readlane_b32 s8, v126, 12
	v_readlane_b32 s9, v126, 13
	v_readlane_b32 s3, v126, 14
	v_mov_b32_e32 v0, 0
	v_mov_b32_e32 v1, 1
	s_lshl_b32 s3, s3, 8
	s_add_u32 s0, s8, s3
	s_addc_u32 s1, s9, 0
	s_add_u32 s0, s0, 0x1400
	s_addc_u32 s1, s1, 0
	global_atomic_add v4, v0, v1, s[0:1] sc0
	v_mov_b32_e32 v5, 0x23ff0
	ds_read2_b32 v[2:3], v5 offset1:1
	s_add_u32 s8, s8, 0x3400
	s_addc_u32 s9, s9, 0
	s_sub_i32 s3, 16, s90
	s_mov_b32 s7, 0
	s_waitcnt lgkmcnt(0)
	v_readfirstlane_b32 s1, v2
	v_readfirstlane_b32 s6, v3
	s_mul_i32 s1, s1, s3
	s_mul_i32 s6, s6, s3
	s_waitcnt vmcnt(0)
	v_readfirstlane_b32 s0, v4
	s_add_i32 s0, s0, 1
	s_cmp_lg_u32 s0, s1
	s_cbranch_scc1 .Lgb15_poll
	buffer_wbl2 sc1
	s_waitcnt vmcnt(0)
	global_atomic_add v0, v1, s[8:9]

.LBB0_1521:
	s_cmp_lt_i32 s91, 18
	s_cbranch_scc1 .LBB0_1575
	s_waitcnt vmcnt(0)
	s_waitcnt vmcnt(0) lgkmcnt(0)
	s_barrier
	s_mov_b64 s[4:5], exec
	v_readlane_b32 s0, v126, 10
	v_readlane_b32 s1, v126, 11
	s_and_b64 s[0:1], s[4:5], s[0:1]
	s_mov_b64 exec, s[0:1]
	s_cbranch_execz .LBB0_1574
	v_readlane_b32 s8, v126, 12
	v_readlane_b32 s9, v126, 13
	v_readlane_b32 s3, v126, 14
	v_mov_b32_e32 v0, 0
	v_mov_b32_e32 v1, 1
	s_lshl_b32 s3, s3, 8
	s_add_u32 s0, s8, s3
	s_addc_u32 s1, s9, 0
	s_add_u32 s0, s0, 0x1400
	s_addc_u32 s1, s1, 0
	global_atomic_add v4, v0, v1, s[0:1] sc0
	v_mov_b32_e32 v5, 0x23ff0
	ds_read2_b32 v[2:3], v5 offset1:1
	s_add_u32 s8, s8, 0x3400
	s_addc_u32 s9, s9, 0
	s_sub_i32 s3, 17, s90
	s_mov_b32 s7, 0
	s_waitcnt lgkmcnt(0)
	v_readfirstlane_b32 s1, v2
	v_readfirstlane_b32 s6, v3
	s_mul_i32 s1, s1, s3
	s_mul_i32 s6, s6, s3
	s_waitcnt vmcnt(0)
	v_readfirstlane_b32 s0, v4
	s_add_i32 s0, s0, 1
	s_cmp_lg_u32 s0, s1
	s_cbranch_scc1 .Lgb16_poll
	buffer_wbl2 sc1
	s_waitcnt vmcnt(0)
	global_atomic_add v0, v1, s[8:9]

.LBB0_1592:
	s_cmp_lt_i32 s91, 19
	s_cbranch_scc1 .LBB0_1646
	s_waitcnt vmcnt(0)
	s_waitcnt vmcnt(0) lgkmcnt(0)
	s_barrier
	s_mov_b64 s[4:5], exec
	v_readlane_b32 s0, v126, 10
	v_readlane_b32 s1, v126, 11
	s_and_b64 s[0:1], s[4:5], s[0:1]
	s_mov_b64 exec, s[0:1]
	s_cbranch_execz .LBB0_1645
	v_readlane_b32 s8, v126, 12
	v_readlane_b32 s9, v126, 13
	v_readlane_b32 s3, v126, 14
	v_mov_b32_e32 v0, 0
	v_mov_b32_e32 v1, 1
	s_lshl_b32 s3, s3, 8
	s_add_u32 s0, s8, s3
	s_addc_u32 s1, s9, 0
	s_add_u32 s0, s0, 0x1400
	s_addc_u32 s1, s1, 0
	global_atomic_add v4, v0, v1, s[0:1] sc0
	v_mov_b32_e32 v5, 0x23ff0
	ds_read2_b32 v[2:3], v5 offset1:1
	s_add_u32 s8, s8, 0x3400
	s_addc_u32 s9, s9, 0
	s_sub_i32 s3, 18, s90
	s_mov_b32 s7, 0
	s_waitcnt lgkmcnt(0)
	v_readfirstlane_b32 s1, v2
	v_readfirstlane_b32 s6, v3
	s_mul_i32 s1, s1, s3
	s_mul_i32 s6, s6, s3
	s_waitcnt vmcnt(0)
	v_readfirstlane_b32 s0, v4
	s_add_i32 s0, s0, 1
	s_cmp_lg_u32 s0, s1
	s_cbranch_scc1 .Lgb17_poll
	buffer_wbl2 sc1
	s_waitcnt vmcnt(0)
	global_atomic_add v0, v1, s[8:9]
